# phase-0 row items: second row's loads issued with the first row's, norm gain vector served from a per-wave LDS copy (LDS-DMA) instead of 8 global re-reads with full vmcnt waits
# speedup vs baseline: 1.2451x; 1.0020x over previous
.LBB0_33:
	s_or_b64 exec, exec, s[4:5]
	v_writelane_b32 v252, s60, 8
	s_cmpk_gt_i32 s2, 0xe2f
	v_and_b32_e32 v161, 63, v162
	v_writelane_b32 v252, s61, 9
	v_writelane_b32 v252, s62, 10
	v_writelane_b32 v252, s63, 11
	v_writelane_b32 v252, s64, 12
	v_writelane_b32 v252, s65, 13
	v_writelane_b32 v252, s66, 14
	v_writelane_b32 v252, s67, 15
	v_writelane_b32 v252, s68, 16
	v_writelane_b32 v252, s69, 17
	v_writelane_b32 v252, s70, 18
	v_writelane_b32 v252, s71, 19
	v_writelane_b32 v252, s72, 20
	v_writelane_b32 v252, s73, 21
	v_lshrrev_b32_e32 v160, 6, v162
	v_lshrrev_b32_e32 v228, 5, v162
	v_lshlrev_b32_e32 v229, 2, v162
	v_mbcnt_lo_u32_b32 v230, -1, 0
	v_writelane_b32 v252, s74, 22
	v_writelane_b32 v252, s75, 23
	s_cbranch_scc1 .LBB0_59
	s_load_dword s11, s[0:1], 0x1b8
	s_waitcnt lgkmcnt(0)
	s_load_dwordx16 s[12:27], s[0:1], 0xc0
	v_lshlrev_b32_e32 v1, 2, v162
	v_mov_b32_e32 v167, 0
	v_and_b32_e32 v166, 0x7c, v1
	s_movk_i32 s4, 0x84
	s_waitcnt lgkmcnt(0)
	v_lshl_add_u64 v[170:171], s[16:17], 0, v[166:167]
	s_load_dwordx8 s[16:23], s[0:1], 0x180
	v_lshl_add_u64 v[174:175], s[12:13], 0, v[166:167]
	v_lshlrev_b32_e32 v0, 2, v161
	v_lshlrev_b32_e32 v168, 4, v161
	v_mul_u32_u24_e32 v1, 0x74, v161
	s_waitcnt lgkmcnt(0)
	s_mov_b64 s[58:59], s[22:23]
	s_mov_b64 s[56:57], s[20:21]
	s_mov_b64 s[54:55], s[18:19]
	s_mov_b64 s[52:53], s[16:17]
	s_load_dwordx16 s[12:27], s[0:1], 0x80
	v_lshlrev_b32_e32 v2, 2, v160
	v_mad_u32_u24 v231, v228, s4, v166
	s_lshl_b32 s4, s2, 3
	v_mbcnt_hi_u32_b32 v232, -1, v230
	s_waitcnt lgkmcnt(0)
	v_lshl_add_u64 v[178:179], s[24:25], 0, v[166:167]
	v_lshl_add_u64 v[182:183], s[14:15], 0, v[166:167]
	s_load_dwordx16 s[12:27], s[0:1], 0x140
	v_add3_u32 v163, v168, v1, v2
	v_lshlrev_b32_e32 v2, 1, v161
	v_mov_b32_e32 v3, v167
	v_lshl_add_u64 v[186:187], s[36:37], 0, v[166:167]
	v_mov_b32_e32 v169, v167
	v_lshlrev_b32_e32 v166, 3, v161
	s_waitcnt lgkmcnt(0)
	s_add_i32 s12, s4, 0x7ffff000
	s_lshl_b32 s4, s2, 4
	v_lshlrev_b32_e32 v194, 2, v0
	v_and_b32_e32 v0, 64, v232
	v_lshl_add_u64 v[172:173], s[56:57], 0, v[2:3]
	v_lshl_add_u64 v[176:177], s[54:55], 0, v[2:3]
	v_lshl_add_u64 v[180:181], s[52:53], 0, v[2:3]
	v_lshl_add_u64 v[184:185], s[26:27], 0, v[2:3]
	v_lshl_add_u64 v[188:189], s[24:25], 0, v[2:3]
	v_lshl_add_u64 v[190:191], s[74:75], 0, v[168:169]
	v_readfirstlane_b32 s98, v160
	s_nop 3
	s_lshl_b32 s98, s98, 12
	s_add_u32 s98, s98, 0xb000
	s_mov_b32 m0, s98
	v_lshl_add_u32 v250, v161, 4, s98
	global_load_lds_dwordx4 v[190:191], off
	global_load_lds_dwordx4 v[190:191], off offset:1024
	global_load_lds_dwordx4 v[190:191], off offset:2048
	global_load_lds_dwordx4 v[190:191], off offset:3072
	v_lshl_add_u64 v[192:193], s[58:59], 0, v[166:167]
	s_add_i32 s13, s4, 0x7fffec00
	v_mov_b32_e32 v169, 0x358637bd
	v_add_u32_e32 v233, 64, v0
	v_xor_b32_e32 v234, 32, v232
	v_xor_b32_e32 v235, 16, v232
	v_xor_b32_e32 v236, 8, v232
	v_xor_b32_e32 v237, 4, v232
	v_xor_b32_e32 v238, 2, v232
	v_xor_b32_e32 v239, 1, v232
	s_lshl_b32 s14, s11, 3
	s_lshl_b32 s15, s11, 8
	s_lshl_b32 s16, s11, 4
	s_movk_i32 s17, 0x4000
	s_mov_b32 s18, 0x800000
	s_mov_b32 s19, 0x10000
	s_mov_b32 s20, 0x28000
	s_mov_b32 s21, 0x50000
	s_mov_b32 s22, 0x58000
	s_mov_b32 s23, 0x78000
	s_mov_b32 s24, 0xa0000
	s_mov_b32 s25, 0xb0000
	s_mov_b32 s26, 0xc8000
	s_mov_b32 s27, 0xf0000
	s_mov_b32 s33, s2
	s_mov_b32 s7, 0
	v_cmp_eq_u32_e64 s[4:5], 0, v161
	s_branch .LBB0_36

.LBB0_36:
	s_cmpk_gt_i32 s33, 0x61f
	s_mov_b64 s[8:9], -1
	s_cbranch_scc0 .LBB0_42
	v_add_u32_e32 v8, s12, v160
	v_add_u32_e32 v196, 0x7fffdf00, v8
	v_add_u32_e32 v0, 0x7fff9f00, v8
	v_cmp_gt_i32_e32 vcc, s17, v196
	s_waitcnt lgkmcnt(0)
	v_mov_b32_e32 v26, s63
	v_mov_b32_e32 v27, s61
	v_cndmask_b32_e32 v166, v0, v196, vcc
	v_mov_b32_e32 v28, s62
	v_mov_b32_e32 v29, s60
	v_cndmask_b32_e32 v1, v26, v27, vcc
	v_cndmask_b32_e32 v0, v28, v29, vcc
	v_lshlrev_b64 v[2:3], 12, v[166:167]
	v_lshl_add_u64 v[0:1], v[0:1], 0, v[2:3]
	v_mov_b32_e32 v195, v167
	v_lshl_add_u64 v[4:5], v[0:1], 0, v[194:195]
	global_load_dwordx4 v[0:3], v[4:5], off
	global_load_dwordx4 v[136:139], v[4:5], off offset:1024
	global_load_dwordx4 v[132:135], v[4:5], off offset:2048
	global_load_dwordx4 v[128:131], v[4:5], off offset:3072
	v_cmp_lt_i32_e32 vcc, v234, v233
	ds_read_b128 v[4:7], v250
	s_movk_i32 s6, 0x3ffc
	v_cmp_gt_i32_e64 s[98:99], s6, v196
	v_add_u32_e32 v72, 0x7fffdf04, v8
	v_add_u32_e32 v73, 0x7fff9f04, v8
	v_cndmask_b32_e64 v72, v73, v72, s[98:99]
	v_mov_b32_e32 v73, v167
	v_cndmask_b32_e64 v75, v26, v27, s[98:99]
	v_cndmask_b32_e64 v74, v28, v29, s[98:99]
	v_lshlrev_b64 v[72:73], 12, v[72:73]
	v_lshl_add_u64 v[72:73], v[74:75], 0, v[72:73]
	v_lshl_add_u64 v[72:73], v[72:73], 0, v[194:195]
	global_load_dwordx4 v[124:127], v[72:73], off
	global_load_dwordx4 v[88:91], v[72:73], off offset:1024
	global_load_dwordx4 v[84:87], v[72:73], off offset:2048
	global_load_dwordx4 v[72:75], v[72:73], off offset:3072
	s_movk_i32 s6, 0x3ffc
	v_cndmask_b32_e32 v10, v232, v234, vcc
	v_lshlrev_b32_e32 v240, 2, v10
	v_cmp_lt_i32_e32 vcc, v235, v233
	v_mov_b32_e32 v197, v167
	v_add_u32_e32 v166, 0x7fffdf04, v8
	v_mov_b32_e32 v9, v167
	s_waitcnt vmcnt(7)
	v_mov_b32_e32 v16, v1
	s_waitcnt vmcnt(6)
	v_mov_b32_e32 v17, v137
	v_mov_b32_e32 v14, v0
	v_mov_b32_e32 v15, v136
	s_waitcnt vmcnt(5)
	v_mov_b32_e32 v24, v133
	s_waitcnt vmcnt(4)
	v_mov_b32_e32 v25, v129
	v_pk_mul_f32 v[16:17], v[16:17], v[16:17]
	v_mov_b32_e32 v10, v2
	v_mov_b32_e32 v11, v138
	v_mov_b32_e32 v22, v132
	v_mov_b32_e32 v23, v128
	v_pk_mul_f32 v[24:25], v[24:25], v[24:25]
	v_pk_fma_f32 v[14:15], v[14:15], v[14:15], v[16:17]
	v_mov_b32_e32 v12, v3
	v_mov_b32_e32 v13, v139
	v_mov_b32_e32 v18, v134
	v_mov_b32_e32 v19, v130
	v_pk_fma_f32 v[16:17], v[22:23], v[22:23], v[24:25]
	v_pk_fma_f32 v[10:11], v[10:11], v[10:11], v[14:15]
	v_mov_b32_e32 v20, v135
	v_mov_b32_e32 v21, v131
	v_pk_fma_f32 v[14:15], v[18:19], v[18:19], v[16:17]
	v_pk_fma_f32 v[10:11], v[12:13], v[12:13], v[10:11]
	v_pk_fma_f32 v[12:13], v[20:21], v[20:21], v[14:15]
	v_add_f32_e32 v10, v10, v11
	v_add_f32_e32 v10, v10, v12
	v_add_f32_e32 v10, v10, v13
	ds_bpermute_b32 v11, v240, v10
	v_cndmask_b32_e32 v12, v232, v235, vcc
	v_lshlrev_b32_e32 v244, 2, v12
	v_cmp_lt_i32_e32 vcc, v236, v233
	v_add_u32_e32 v15, 0x7fff9f04, v8
	s_waitcnt lgkmcnt(0)
	v_add_f32_e32 v10, v10, v11
	ds_bpermute_b32 v11, v244, v10
	v_cndmask_b32_e32 v13, v232, v236, vcc
	v_lshlrev_b32_e32 v243, 2, v13
	v_cmp_lt_i32_e32 vcc, v237, v233
	s_waitcnt lgkmcnt(0)
	v_add_f32_e32 v10, v10, v11
	ds_bpermute_b32 v11, v243, v10
	v_cndmask_b32_e32 v12, v232, v237, vcc
	v_lshlrev_b32_e32 v245, 2, v12
	v_cmp_lt_i32_e32 vcc, v238, v233
	s_waitcnt lgkmcnt(0)
	v_add_f32_e32 v12, v10, v11
	ds_bpermute_b32 v16, v245, v12
	v_cndmask_b32_e32 v14, v232, v238, vcc
	v_cmp_lt_i32_e32 vcc, v239, v233
	v_lshlrev_b32_e32 v242, 2, v14
	v_lshlrev_b64 v[10:11], 11, v[196:197]
	v_cndmask_b32_e32 v13, v232, v239, vcc
	s_waitcnt lgkmcnt(0)
	v_add_f32_e32 v12, v12, v16
	v_lshlrev_b32_e32 v241, 2, v13
	ds_bpermute_b32 v13, v242, v12
	v_cmp_gt_i32_e32 vcc, s6, v196
	v_lshl_add_u64 v[216:217], v[192:193], 0, v[10:11]
	s_waitcnt lgkmcnt(0)
	v_add_f32_e32 v12, v12, v13
	ds_bpermute_b32 v13, v241, v12
	v_cndmask_b32_e32 v8, v15, v166, vcc
	v_cndmask_b32_e32 v11, v26, v27, vcc
	v_cndmask_b32_e32 v10, v28, v29, vcc
	v_lshlrev_b64 v[8:9], 12, v[8:9]
	v_lshl_add_u64 v[8:9], v[10:11], 0, v[8:9]
	s_waitcnt lgkmcnt(0)
	v_add_f32_e32 v10, v12, v13
	v_fmamk_f32 v10, v10, 0x3a800000, v169
	v_mul_f32_e32 v11, 0x4b800000, v10
	v_cmp_gt_f32_e32 vcc, s18, v10
	v_lshl_add_u64 v[8:9], v[8:9], 0, v[194:195]
	s_nop 0
	s_nop 0
	s_nop 0
	s_nop 0
	v_cndmask_b32_e32 v10, v10, v11, vcc
	v_rsq_f32_e32 v10, v10
	s_nop 0
	v_mul_f32_e32 v8, 0x45800000, v10
	v_cndmask_b32_e32 v218, v10, v8, vcc
	s_waitcnt lgkmcnt(0)
	v_pk_mul_f32 v[4:5], v[4:5], v[218:219] op_sel_hi:[1,0]
	v_pk_mul_f32 v[6:7], v[6:7], v[218:219] op_sel_hi:[1,0]
	v_pk_mul_f32 v[222:223], v[0:1], v[4:5]
	v_pk_mul_f32 v[220:221], v[2:3], v[6:7]
	v_cvt_pk_bf16_f32 v0, v222, v223
	v_cvt_pk_bf16_f32 v1, v220, v221
	global_store_dwordx2 v[216:217], v[0:1], off
	ds_read_b128 v[140:143], v250 offset:1024
	ds_read_b128 v[108:111], v168
	ds_read_b128 v[92:95], v168 offset:1024
	ds_read_b128 v[64:67], v168 offset:4096
	ds_read_b128 v[60:63], v168 offset:5120
	ds_read_b128 v[112:115], v168 offset:8192
	ds_read_b128 v[96:99], v168 offset:9216
	ds_read_b128 v[44:47], v168 offset:12288
	ds_read_b128 v[40:43], v168 offset:13312
	ds_read_b128 v[116:119], v168 offset:16384
	ds_read_b128 v[100:103], v168 offset:17408
	ds_read_b128 v[24:27], v168 offset:20480
	ds_read_b128 v[20:23], v168 offset:21504
	ds_read_b128 v[120:123], v168 offset:24576
	ds_read_b128 v[104:107], v168 offset:25600
	ds_read_b128 v[16:19], v168 offset:28672
	ds_read_b128 v[12:15], v168 offset:29696
	ds_read_b128 v[76:79], v168 offset:2048
	ds_read_b128 v[156:159], v168 offset:3072
	ds_read_b128 v[80:83], v168 offset:6144
	ds_read_b128 v[68:71], v168 offset:7168
	ds_read_b128 v[52:55], v168 offset:10240
	ds_read_b128 v[152:155], v168 offset:11264
	ds_read_b128 v[56:59], v168 offset:14336
	ds_read_b128 v[48:51], v168 offset:15360
	ds_read_b128 v[32:35], v168 offset:18432
	ds_read_b128 v[148:151], v168 offset:19456
	ds_read_b128 v[36:39], v168 offset:22528
	ds_read_b128 v[28:31], v168 offset:23552
	ds_read_b128 v[8:11], v168 offset:26624
	ds_read_b128 v[144:147], v168 offset:27648
	ds_read_b128 v[4:7], v168 offset:30720
	ds_read_b128 v[0:3], v168 offset:31744
	s_waitcnt lgkmcnt(14)
	v_mov_b32_e32 v210, v16
	v_mov_b32_e32 v211, v121
	v_mov_b32_e32 v121, v17
	v_mov_b32_e32 v212, v122
	v_mov_b32_e32 v213, v18
	v_mov_b32_e32 v18, v123
	v_mov_b32_e32 v122, v20
	v_mov_b32_e32 v123, v101
	v_mov_b32_e32 v101, v21
	v_mov_b32_e32 v226, v109
	v_mov_b32_e32 v227, v65
	v_mov_b32_e32 v224, v108
	v_mov_b32_e32 v225, v64
	v_mov_b32_e32 v202, v44
	v_mov_b32_e32 v203, v113
	v_mov_b32_e32 v206, v24
	v_mov_b32_e32 v207, v117
	v_mov_b32_e32 v200, v110
	v_mov_b32_e32 v201, v66
	v_mov_b32_e32 v66, v111
	v_mov_b32_e32 v113, v45
	v_mov_b32_e32 v117, v25
	s_waitcnt lgkmcnt(13)
	v_mov_b32_e32 v110, v80
	v_mov_b32_e32 v111, v77
	v_mov_b32_e32 v77, v81
	s_waitcnt lgkmcnt(9)
	v_mov_b32_e32 v214, v56
	v_mov_b32_e32 v215, v53
	v_mov_b32_e32 v53, v57
	s_waitcnt lgkmcnt(8)
	v_pk_mov_b32 v[56:57], v[152:153], v[48:49] op_sel:[1,0]
	v_pk_mov_b32 v[80:81], v[48:49], v[152:153] op_sel:[1,0]
	s_waitcnt lgkmcnt(4)
	v_pk_mov_b32 v[44:45], v[148:149], v[28:29] op_sel:[1,0]
	v_pk_mov_b32 v[48:49], v[28:29], v[148:149] op_sel:[1,0]
	v_mov_b32_e32 v28, v150
	v_mov_b32_e32 v29, v30
	v_mov_b32_e32 v30, v151
	v_pk_mul_f32 v[148:149], v[222:223], v[206:207]
	v_pk_mul_f32 v[150:151], v[222:223], v[210:211]
	v_mov_b32_e32 v204, v114
	v_mov_b32_e32 v205, v46
	v_mov_b32_e32 v46, v115
	v_mov_b32_e32 v208, v118
	v_mov_b32_e32 v209, v26
	v_mov_b32_e32 v26, v119
	v_mov_b32_e32 v114, v60
	v_mov_b32_e32 v115, v93
	v_mov_b32_e32 v118, v40
	v_mov_b32_e32 v119, v97
	v_pk_fma_f32 v[148:149], v[222:223], v[116:117], v[148:149] op_sel:[0,0,1] op_sel_hi:[1,1,0]
	v_pk_fma_f32 v[150:151], v[222:223], v[120:121], v[150:151] op_sel:[0,0,1] op_sel_hi:[1,1,0]
	v_mov_b32_e32 v93, v61
	v_mov_b32_e32 v97, v41
	v_mov_b32_e32 v198, v12
	v_mov_b32_e32 v199, v105
	v_pk_fma_f32 v[148:149], v[220:221], v[208:209], v[148:149] op_sel_hi:[0,1,1]
	v_pk_fma_f32 v[150:151], v[220:221], v[212:213], v[150:151] op_sel_hi:[0,1,1]
	v_mov_b32_e32 v60, v94
	v_mov_b32_e32 v61, v62
	v_mov_b32_e32 v40, v98
	v_mov_b32_e32 v41, v42
	v_mov_b32_e32 v105, v13
	v_pk_fma_f32 v[148:149], v[220:221], v[26:27], v[148:149] op_sel:[1,0,0]
	v_pk_fma_f32 v[150:151], v[220:221], v[18:19], v[150:151] op_sel:[1,0,0]
	v_mov_b32_e32 v12, v106
	v_mov_b32_e32 v13, v14
	v_mov_b32_e32 v62, v95
	v_mov_b32_e32 v42, v99
	v_mov_b32_e32 v24, v102
	v_mov_b32_e32 v25, v22
	v_mov_b32_e32 v22, v103
	v_mov_b32_e32 v14, v107
	s_waitcnt lgkmcnt(0)
	v_pk_mul_f32 v[16:17], v[218:219], v[140:141] op_sel_hi:[0,1]
	v_pk_mul_f32 v[20:21], v[218:219], v[142:143] op_sel_hi:[0,1]
	v_pk_mul_f32 v[246:247], v[136:137], v[16:17]
	v_pk_mul_f32 v[248:249], v[138:139], v[20:21]
	v_cvt_pk_bf16_f32 v16, v246, v247
	v_cvt_pk_bf16_f32 v17, v248, v249
	global_store_dwordx2 v[216:217], v[16:17], off offset:512
	ds_read_b128 v[136:139], v250 offset:2048
	s_waitcnt lgkmcnt(0)
	v_pk_mov_b32 v[16:17], v[144:145], v[0:1] op_sel:[1,0]
	v_pk_mov_b32 v[20:21], v[0:1], v[144:145] op_sel:[1,0]
	v_pk_mul_f32 v[144:145], v[222:223], v[226:227] op_sel:[1,0]
	v_mov_b32_e32 v0, v146
	v_mov_b32_e32 v1, v2
	v_mov_b32_e32 v2, v147
	v_pk_mul_f32 v[146:147], v[222:223], v[202:203]
	v_pk_fma_f32 v[144:145], v[222:223], v[224:225], v[144:145] op_sel_hi:[0,1,1]
	v_pk_fma_f32 v[146:147], v[222:223], v[112:113], v[146:147] op_sel:[0,0,1] op_sel_hi:[1,1,0]
	v_pk_fma_f32 v[144:145], v[200:201], v[220:221], v[144:145] op_sel_hi:[1,0,1]
	v_pk_mov_b32 v[140:141], v[156:157], v[68:69] op_sel:[1,0]
	v_pk_mov_b32 v[156:157], v[68:69], v[156:157] op_sel:[1,0]
	v_mov_b32_e32 v68, v154
	v_mov_b32_e32 v69, v50
	v_mov_b32_e32 v50, v155
	v_pk_fma_f32 v[146:147], v[220:221], v[204:205], v[146:147] op_sel_hi:[0,1,1]
	v_pk_fma_f32 v[152:153], v[66:67], v[220:221], v[144:145] op_sel:[0,1,0]
	v_pk_mul_f32 v[144:145], v[246:247], v[114:115]
	v_pk_mul_f32 v[154:155], v[246:247], v[118:119]
	v_pk_fma_f32 v[146:147], v[220:221], v[46:47], v[146:147] op_sel:[1,0,0]
	v_pk_mul_f32 v[220:221], v[246:247], v[198:199]
	v_pk_fma_f32 v[222:223], v[246:247], v[92:93], v[144:145] op_sel:[0,0,1] op_sel_hi:[1,1,0]
	v_pk_fma_f32 v[154:155], v[246:247], v[96:97], v[154:155] op_sel:[0,0,1] op_sel_hi:[1,1,0]
	v_mov_b32_e32 v142, v158
	v_mov_b32_e32 v143, v70
	v_mov_b32_e32 v70, v159
	v_pk_mul_f32 v[158:159], v[246:247], v[122:123]
	v_pk_fma_f32 v[220:221], v[246:247], v[104:105], v[220:221] op_sel:[0,0,1] op_sel_hi:[1,1,0]
	v_mov_b32_e32 v144, v36
	v_mov_b32_e32 v145, v33
	v_mov_b32_e32 v33, v37
	v_pk_fma_f32 v[36:37], v[248:249], v[60:61], v[222:223] op_sel_hi:[0,1,1]
	v_pk_fma_f32 v[94:95], v[248:249], v[40:41], v[154:155] op_sel_hi:[0,1,1]
	v_pk_fma_f32 v[158:159], v[246:247], v[100:101], v[158:159] op_sel:[0,0,1] op_sel_hi:[1,1,0]
	v_pk_fma_f32 v[102:103], v[248:249], v[12:13], v[220:221] op_sel_hi:[0,1,1]
	v_pk_fma_f32 v[36:37], v[248:249], v[62:63], v[36:37] op_sel:[1,0,0]
	v_pk_fma_f32 v[106:107], v[248:249], v[42:43], v[94:95] op_sel:[1,0,0]
	v_mov_b32_e32 v94, v4
	v_mov_b32_e32 v95, v9
	v_mov_b32_e32 v9, v5
	v_pk_add_f32 v[4:5], v[152:153], 0 op_sel_hi:[1,0]
	v_pk_fma_f32 v[98:99], v[248:249], v[24:25], v[158:159] op_sel_hi:[0,1,1]
	v_pk_fma_f32 v[154:155], v[248:249], v[14:15], v[102:103] op_sel:[1,0,0]
	v_pk_add_f32 v[102:103], v[4:5], v[36:37]
	v_pk_add_f32 v[4:5], v[146:147], 0 op_sel_hi:[1,0]
	v_pk_fma_f32 v[98:99], v[248:249], v[22:23], v[98:99] op_sel:[1,0,0]
	v_pk_add_f32 v[106:107], v[4:5], v[106:107]
	v_mov_b32_e32 v4, v54
	v_mov_b32_e32 v5, v58
	v_mov_b32_e32 v58, v55
	v_pk_add_f32 v[54:55], v[148:149], 0 op_sel_hi:[1,0]
	v_mov_b32_e32 v36, v78
	v_mov_b32_e32 v37, v82
	v_mov_b32_e32 v82, v79
	v_pk_add_f32 v[78:79], v[54:55], v[98:99]
	v_pk_add_f32 v[146:147], v[150:151], 0 op_sel_hi:[1,0]
	s_waitcnt lgkmcnt(0)
	v_pk_mul_f32 v[54:55], v[218:219], v[136:137] op_sel_hi:[0,1]
	v_pk_mul_f32 v[136:137], v[218:219], v[138:139] op_sel_hi:[0,1]
	v_pk_mul_f32 v[54:55], v[132:133], v[54:55]
	v_pk_mul_f32 v[132:133], v[134:135], v[136:137]
	v_cvt_pk_bf16_f32 v134, v54, v55
	v_cvt_pk_bf16_f32 v135, v132, v133
	v_pk_add_f32 v[98:99], v[146:147], v[154:155]
	v_pk_mul_f32 v[136:137], v[54:55], v[110:111]
	v_pk_mul_f32 v[138:139], v[54:55], v[214:215]
	v_pk_mul_f32 v[146:147], v[54:55], v[144:145]
	global_store_dwordx2 v[216:217], v[134:135], off offset:1024
	v_pk_mul_f32 v[134:135], v[54:55], v[94:95]
	v_pk_fma_f32 v[136:137], v[54:55], v[76:77], v[136:137] op_sel:[0,0,1] op_sel_hi:[1,1,0]
	v_pk_fma_f32 v[138:139], v[54:55], v[52:53], v[138:139] op_sel:[0,0,1] op_sel_hi:[1,1,0]
	v_pk_fma_f32 v[146:147], v[54:55], v[32:33], v[146:147] op_sel:[0,0,1] op_sel_hi:[1,1,0]
	v_pk_fma_f32 v[134:135], v[54:55], v[8:9], v[134:135] op_sel:[0,0,1] op_sel_hi:[1,1,0]
	v_mov_b32_e32 v54, v34
	v_mov_b32_e32 v55, v38
	v_mov_b32_e32 v38, v35
	v_mov_b32_e32 v34, v10
	v_mov_b32_e32 v35, v6
	v_mov_b32_e32 v6, v11
	v_pk_fma_f32 v[10:11], v[132:133], v[36:37], v[136:137] op_sel_hi:[0,1,1]
	v_pk_fma_f32 v[136:137], v[132:133], v[4:5], v[138:139] op_sel_hi:[0,1,1]
	v_pk_fma_f32 v[138:139], v[132:133], v[54:55], v[146:147] op_sel_hi:[0,1,1]
	v_pk_fma_f32 v[134:135], v[132:133], v[34:35], v[134:135] op_sel_hi:[0,1,1]
	v_pk_fma_f32 v[10:11], v[132:133], v[82:83], v[10:11] op_sel:[1,0,0]
	v_pk_fma_f32 v[136:137], v[132:133], v[58:59], v[136:137] op_sel:[1,0,0]
	v_pk_fma_f32 v[138:139], v[132:133], v[38:39], v[138:139] op_sel:[1,0,0]
	v_pk_fma_f32 v[146:147], v[132:133], v[6:7], v[134:135] op_sel:[1,0,0]
	ds_read_b128 v[132:135], v250 offset:3072
	v_pk_add_f32 v[10:11], v[102:103], v[10:11]
	v_pk_add_f32 v[102:103], v[106:107], v[136:137]
	v_pk_add_f32 v[78:79], v[78:79], v[138:139]
	v_pk_add_f32 v[98:99], v[98:99], v[146:147]
	s_waitcnt lgkmcnt(0)
	v_pk_mul_f32 v[106:107], v[218:219], v[132:133] op_sel_hi:[0,1]
	v_pk_mul_f32 v[132:133], v[218:219], v[134:135] op_sel_hi:[0,1]
	v_pk_mul_f32 v[134:135], v[128:129], v[106:107]
	v_pk_mul_f32 v[136:137], v[130:131], v[132:133]
	v_pk_mul_f32 v[106:107], v[134:135], v[156:157] op_sel:[1,0] op_sel_hi:[0,1]
	v_pk_mul_f32 v[128:129], v[134:135], v[80:81] op_sel:[1,0] op_sel_hi:[0,1]
	v_pk_mul_f32 v[130:131], v[134:135], v[48:49] op_sel:[1,0] op_sel_hi:[0,1]
	v_pk_mul_f32 v[132:133], v[134:135], v[20:21] op_sel:[1,0] op_sel_hi:[0,1]
	v_pk_fma_f32 v[106:107], v[134:135], v[140:141], v[106:107] op_sel:[1,0,1] op_sel_hi:[0,1,0]
	v_pk_fma_f32 v[128:129], v[134:135], v[56:57], v[128:129] op_sel:[1,0,1] op_sel_hi:[0,1,0]
	v_pk_fma_f32 v[130:131], v[134:135], v[44:45], v[130:131] op_sel:[1,0,1] op_sel_hi:[0,1,0]
	v_pk_fma_f32 v[132:133], v[134:135], v[16:17], v[132:133] op_sel:[1,0,1] op_sel_hi:[0,1,0]
	v_pk_fma_f32 v[106:107], v[136:137], v[142:143], v[106:107] op_sel_hi:[0,1,1]
	v_pk_fma_f32 v[128:129], v[136:137], v[68:69], v[128:129] op_sel_hi:[0,1,1]
	v_pk_fma_f32 v[130:131], v[136:137], v[28:29], v[130:131] op_sel_hi:[0,1,1]
	v_pk_fma_f32 v[132:133], v[136:137], v[0:1], v[132:133] op_sel_hi:[0,1,1]
	v_pk_fma_f32 v[106:107], v[136:137], v[70:71], v[106:107] op_sel:[1,0,0]
	v_pk_fma_f32 v[128:129], v[136:137], v[50:51], v[128:129] op_sel:[1,0,0]
	v_pk_fma_f32 v[130:131], v[136:137], v[30:31], v[130:131] op_sel:[1,0,0]
	v_pk_fma_f32 v[132:133], v[136:137], v[2:3], v[132:133] op_sel:[1,0,0]
	v_pk_add_f32 v[10:11], v[10:11], v[106:107]
	v_pk_add_f32 v[102:103], v[102:103], v[128:129]
	v_pk_add_f32 v[78:79], v[78:79], v[130:131]
	v_pk_add_f32 v[98:99], v[98:99], v[132:133]
	ds_bpermute_b32 v106, v240, v10
	ds_bpermute_b32 v107, v240, v11
	ds_bpermute_b32 v128, v240, v102
	ds_bpermute_b32 v129, v240, v103
	ds_bpermute_b32 v130, v240, v78
	ds_bpermute_b32 v131, v240, v79
	ds_bpermute_b32 v132, v240, v98
	ds_bpermute_b32 v133, v240, v99
	s_waitcnt lgkmcnt(6)
	v_pk_add_f32 v[10:11], v[10:11], v[106:107]
	s_waitcnt lgkmcnt(4)
	v_pk_add_f32 v[102:103], v[102:103], v[128:129]
	s_waitcnt lgkmcnt(2)
	v_pk_add_f32 v[78:79], v[78:79], v[130:131]
	ds_bpermute_b32 v106, v244, v10
	s_waitcnt lgkmcnt(1)
	v_pk_add_f32 v[98:99], v[98:99], v[132:133]
	ds_bpermute_b32 v107, v244, v11
	ds_bpermute_b32 v128, v244, v102
	ds_bpermute_b32 v129, v244, v103
	ds_bpermute_b32 v130, v244, v78
	ds_bpermute_b32 v131, v244, v79
	ds_bpermute_b32 v132, v244, v98
	ds_bpermute_b32 v133, v244, v99
	s_waitcnt lgkmcnt(6)
	v_pk_add_f32 v[10:11], v[10:11], v[106:107]
	s_waitcnt lgkmcnt(4)
	v_pk_add_f32 v[102:103], v[102:103], v[128:129]
	s_waitcnt lgkmcnt(2)
	v_pk_add_f32 v[78:79], v[78:79], v[130:131]
	ds_bpermute_b32 v106, v243, v10
	s_waitcnt lgkmcnt(1)
	v_pk_add_f32 v[98:99], v[98:99], v[132:133]
	ds_bpermute_b32 v107, v243, v11
	ds_bpermute_b32 v128, v243, v102
	ds_bpermute_b32 v129, v243, v103
	ds_bpermute_b32 v130, v243, v78
	ds_bpermute_b32 v131, v243, v79
	ds_bpermute_b32 v132, v243, v98
	ds_bpermute_b32 v133, v243, v99
	s_waitcnt lgkmcnt(6)
	v_pk_add_f32 v[10:11], v[10:11], v[106:107]
	s_waitcnt lgkmcnt(4)
	v_pk_add_f32 v[102:103], v[102:103], v[128:129]
	s_waitcnt lgkmcnt(2)
	v_pk_add_f32 v[78:79], v[78:79], v[130:131]
	ds_bpermute_b32 v106, v245, v10
	s_waitcnt lgkmcnt(1)
	v_pk_add_f32 v[98:99], v[98:99], v[132:133]
	ds_bpermute_b32 v107, v245, v11
	ds_bpermute_b32 v128, v245, v102
	ds_bpermute_b32 v129, v245, v103
	ds_bpermute_b32 v130, v245, v78
	ds_bpermute_b32 v131, v245, v79
	ds_bpermute_b32 v132, v245, v98
	ds_bpermute_b32 v133, v245, v99
	s_waitcnt lgkmcnt(6)
	v_pk_add_f32 v[10:11], v[10:11], v[106:107]
	s_waitcnt lgkmcnt(4)
	v_pk_add_f32 v[102:103], v[102:103], v[128:129]
	s_waitcnt lgkmcnt(2)
	v_pk_add_f32 v[78:79], v[78:79], v[130:131]
	ds_bpermute_b32 v128, v242, v102
	s_waitcnt lgkmcnt(1)
	v_pk_add_f32 v[106:107], v[98:99], v[132:133]
	ds_bpermute_b32 v98, v242, v10
	ds_bpermute_b32 v99, v242, v11
	ds_bpermute_b32 v129, v242, v103
	ds_bpermute_b32 v130, v242, v78
	ds_bpermute_b32 v131, v242, v79
	ds_bpermute_b32 v132, v242, v106
	ds_bpermute_b32 v133, v242, v107
	s_waitcnt lgkmcnt(5)
	v_pk_add_f32 v[98:99], v[10:11], v[98:99]
	s_waitcnt lgkmcnt(4)
	v_pk_add_f32 v[102:103], v[102:103], v[128:129]
	s_waitcnt lgkmcnt(2)
	v_pk_add_f32 v[10:11], v[78:79], v[130:131]
	ds_bpermute_b32 v130, v241, v98
	s_waitcnt lgkmcnt(1)
	v_pk_add_f32 v[78:79], v[106:107], v[132:133]
	ds_bpermute_b32 v131, v241, v99
	ds_bpermute_b32 v132, v241, v102
	ds_bpermute_b32 v133, v241, v103
	ds_bpermute_b32 v106, v241, v10
	ds_bpermute_b32 v107, v241, v11
	ds_bpermute_b32 v128, v241, v78
	ds_bpermute_b32 v129, v241, v79
	v_cvt_pk_bf16_f32 v134, v134, v135
	v_cvt_pk_bf16_f32 v135, v136, v137
	global_store_dwordx2 v[216:217], v[134:135], off offset:1536
	s_and_saveexec_b64 s[8:9], s[4:5]
	s_cbranch_execz .LBB0_39
	s_load_dwordx16 s[52:67], s[0:1], 0x140
	s_waitcnt lgkmcnt(0)
	s_load_dwordx16 s[60:75], s[0:1], 0x0
	v_lshlrev_b64 v[134:135], 5, v[196:197]
	v_pk_add_f32 v[130:131], v[98:99], v[130:131]
	v_pk_add_f32 v[132:133], v[102:103], v[132:133]
	v_lshl_add_u64 v[134:135], s[58:59], 0, v[134:135]
	global_store_dwordx4 v[134:135], v[130:133], off
	s_nop 1
	v_pk_add_f32 v[130:131], v[10:11], v[106:107]
	v_pk_add_f32 v[132:133], v[78:79], v[128:129]
	global_store_dwordx4 v[134:135], v[130:133], off offset:16
.LBB0_39:
	s_waitcnt vmcnt(4)
	s_or_b64 exec, exec, s[8:9]
	s_waitcnt lgkmcnt(0)
	ds_read_b128 v[128:131], v250
	v_mov_b32_e32 v78, v125
	v_mov_b32_e32 v79, v89
	v_mov_b32_e32 v10, v124
	v_mov_b32_e32 v11, v88
	v_pk_mul_f32 v[78:79], v[78:79], v[78:79]
	v_mov_b32_e32 v98, v85
	v_pk_fma_f32 v[10:11], v[10:11], v[10:11], v[78:79]
	v_mov_b32_e32 v78, v126
	v_mov_b32_e32 v79, v90
	v_pk_fma_f32 v[10:11], v[78:79], v[78:79], v[10:11]
	v_mov_b32_e32 v78, v127
	v_mov_b32_e32 v79, v91
	v_mov_b32_e32 v99, v73
	v_pk_fma_f32 v[10:11], v[78:79], v[78:79], v[10:11]
	v_mov_b32_e32 v78, v84
	v_mov_b32_e32 v79, v72
	v_pk_mul_f32 v[98:99], v[98:99], v[98:99]
	v_add_f32_e32 v10, v10, v11
	v_pk_fma_f32 v[78:79], v[78:79], v[78:79], v[98:99]
	v_mov_b32_e32 v98, v86
	v_mov_b32_e32 v99, v74
	v_pk_fma_f32 v[78:79], v[98:99], v[98:99], v[78:79]
	v_mov_b32_e32 v98, v87
	v_mov_b32_e32 v99, v75
	v_pk_fma_f32 v[78:79], v[98:99], v[98:99], v[78:79]
	s_nop 0
	v_add_f32_e32 v10, v10, v78
	v_add_f32_e32 v10, v10, v79
	ds_bpermute_b32 v11, v240, v10
	v_lshlrev_b64 v[78:79], 11, v[166:167]
	s_waitcnt lgkmcnt(0)
	v_add_f32_e32 v10, v10, v11
	ds_bpermute_b32 v11, v244, v10
	s_waitcnt lgkmcnt(0)
	v_add_f32_e32 v10, v10, v11
	ds_bpermute_b32 v11, v243, v10
	s_waitcnt lgkmcnt(0)
	v_add_f32_e32 v10, v10, v11
	ds_bpermute_b32 v11, v245, v10
	s_waitcnt lgkmcnt(0)
	v_add_f32_e32 v10, v10, v11
	ds_bpermute_b32 v11, v242, v10
	s_waitcnt lgkmcnt(0)
	v_add_f32_e32 v10, v10, v11
	ds_bpermute_b32 v11, v241, v10
	s_waitcnt lgkmcnt(0)
	v_add_f32_e32 v10, v10, v11
	v_fmamk_f32 v10, v10, 0x3a800000, v169
	v_cmp_gt_f32_e32 vcc, s18, v10
	v_mul_f32_e32 v11, 0x4b800000, v10
	s_nop 0
	v_cndmask_b32_e32 v10, v10, v11, vcc
	v_rsq_f32_e32 v10, v10
	s_nop 0
	v_mul_f32_e32 v11, 0x45800000, v10
	v_cndmask_b32_e32 v98, v10, v11, vcc
	s_waitcnt lgkmcnt(0)
	v_pk_mul_f32 v[10:11], v[128:129], v[98:99] op_sel_hi:[1,0]
	s_nop 0
	v_pk_mul_f32 v[124:125], v[124:125], v[10:11]
	v_lshl_add_u64 v[128:129], v[192:193], 0, v[78:79]
	v_pk_mov_b32 v[78:79], v[108:109], v[64:65] op_sel:[1,0]
	v_mov_b32_e32 v109, v65
	v_pk_mul_f32 v[10:11], v[130:131], v[98:99] op_sel_hi:[1,0]
	v_pk_mul_f32 v[64:65], v[108:109], v[124:125]
	v_pk_mul_f32 v[10:11], v[126:127], v[10:11]
	v_pk_fma_f32 v[64:65], v[78:79], v[124:125], v[64:65] op_sel:[0,1,0] op_sel_hi:[1,0,1]
	v_cvt_pk_bf16_f32 v102, v124, v125
	v_pk_fma_f32 v[130:131], v[200:201], v[10:11], v[64:65] op_sel_hi:[1,0,1]
	v_pk_mul_f32 v[64:65], v[202:203], v[124:125]
	v_cvt_pk_bf16_f32 v103, v10, v11
	v_pk_fma_f32 v[64:65], v[112:113], v[124:125], v[64:65] op_sel:[0,0,1] op_sel_hi:[1,1,0]
	global_store_dwordx2 v[128:129], v[102:103], off
	v_pk_fma_f32 v[106:107], v[204:205], v[10:11], v[64:65] op_sel_hi:[1,0,1]
	v_pk_mul_f32 v[64:65], v[206:207], v[124:125]
	v_pk_fma_f32 v[66:67], v[66:67], v[10:11], v[130:131] op_sel:[0,1,0]
	v_pk_fma_f32 v[64:65], v[116:117], v[124:125], v[64:65] op_sel:[0,0,1] op_sel_hi:[1,1,0]
	v_pk_fma_f32 v[46:47], v[46:47], v[10:11], v[106:107] op_sel:[0,1,0]
	v_pk_fma_f32 v[102:103], v[208:209], v[10:11], v[64:65] op_sel_hi:[1,0,1]
	v_pk_mul_f32 v[64:65], v[210:211], v[124:125]
	v_pk_fma_f32 v[26:27], v[26:27], v[10:11], v[102:103] op_sel:[0,1,0]
	v_pk_fma_f32 v[64:65], v[120:121], v[124:125], v[64:65] op_sel:[0,0,1] op_sel_hi:[1,1,0]
	ds_read_b128 v[124:127], v250 offset:1024
	v_pk_fma_f32 v[78:79], v[212:213], v[10:11], v[64:65] op_sel_hi:[1,0,1]
	v_pk_add_f32 v[66:67], v[66:67], 0 op_sel_hi:[1,0]
	v_pk_add_f32 v[46:47], v[46:47], 0 op_sel_hi:[1,0]
	v_pk_add_f32 v[26:27], v[26:27], 0 op_sel_hi:[1,0]
	v_pk_fma_f32 v[10:11], v[18:19], v[10:11], v[78:79] op_sel:[0,1,0]
	s_waitcnt lgkmcnt(0)
	v_pk_mul_f32 v[64:65], v[124:125], v[98:99] op_sel_hi:[1,0]
	s_nop 0
	v_pk_mul_f32 v[64:65], v[88:89], v[64:65]
	v_pk_mul_f32 v[88:89], v[98:99], v[126:127] op_sel_hi:[0,1]
	v_pk_mul_f32 v[88:89], v[90:91], v[88:89]
	v_cvt_pk_bf16_f32 v90, v64, v65
	v_cvt_pk_bf16_f32 v91, v88, v89
	global_store_dwordx2 v[128:129], v[90:91], off offset:512
	v_pk_mul_f32 v[90:91], v[114:115], v[64:65]
	ds_read_b128 v[112:115], v250 offset:2048
	v_pk_fma_f32 v[116:117], v[92:93], v[64:65], v[90:91] op_sel:[0,0,1] op_sel_hi:[1,1,0]
	v_pk_mul_f32 v[90:91], v[118:119], v[64:65]
	v_pk_fma_f32 v[60:61], v[60:61], v[88:89], v[116:117] op_sel_hi:[1,0,1]
	v_pk_fma_f32 v[108:109], v[96:97], v[64:65], v[90:91] op_sel:[0,0,1] op_sel_hi:[1,1,0]
	v_pk_mul_f32 v[90:91], v[122:123], v[64:65]
	v_pk_fma_f32 v[40:41], v[40:41], v[88:89], v[108:109] op_sel_hi:[1,0,1]
	v_pk_fma_f32 v[96:97], v[100:101], v[64:65], v[90:91] op_sel:[0,0,1] op_sel_hi:[1,1,0]
	v_pk_mul_f32 v[90:91], v[198:199], v[64:65]
	v_pk_fma_f32 v[24:25], v[24:25], v[88:89], v[96:97] op_sel_hi:[1,0,1]
	v_pk_fma_f32 v[92:93], v[104:105], v[64:65], v[90:91] op_sel:[0,0,1] op_sel_hi:[1,1,0]
	v_pk_fma_f32 v[60:61], v[62:63], v[88:89], v[60:61] op_sel:[0,1,0]
	v_pk_fma_f32 v[40:41], v[42:43], v[88:89], v[40:41] op_sel:[0,1,0]
	v_pk_fma_f32 v[22:23], v[22:23], v[88:89], v[24:25] op_sel:[0,1,0]
	v_pk_add_f32 v[60:61], v[60:61], v[66:67]
	v_pk_add_f32 v[40:41], v[40:41], v[46:47]
	v_pk_add_f32 v[22:23], v[22:23], v[26:27]
	v_pk_fma_f32 v[12:13], v[12:13], v[88:89], v[92:93] op_sel_hi:[1,0,1]
	v_pk_add_f32 v[10:11], v[10:11], 0 op_sel_hi:[1,0]
	v_pk_fma_f32 v[12:13], v[14:15], v[88:89], v[12:13] op_sel:[0,1,0]
	s_waitcnt lgkmcnt(0)
	v_pk_mul_f32 v[64:65], v[98:99], v[112:113] op_sel_hi:[0,1]
	v_pk_mul_f32 v[90:91], v[84:85], v[64:65]
	v_pk_mul_f32 v[64:65], v[98:99], v[114:115] op_sel_hi:[0,1]
	v_pk_mul_f32 v[84:85], v[86:87], v[64:65]
	v_cvt_pk_bf16_f32 v64, v90, v91
	v_cvt_pk_bf16_f32 v65, v84, v85
	global_store_dwordx2 v[128:129], v[64:65], off offset:1024
	v_pk_mul_f32 v[104:105], v[110:111], v[90:91]
	ds_read_b128 v[110:113], v250 offset:3072
	v_pk_mul_f32 v[114:115], v[214:215], v[90:91]
	v_pk_mul_f32 v[100:101], v[144:145], v[90:91]
	v_pk_mul_f32 v[86:87], v[94:95], v[90:91]
	v_pk_fma_f32 v[62:63], v[76:77], v[90:91], v[104:105] op_sel:[0,0,1] op_sel_hi:[1,1,0]
	v_pk_fma_f32 v[42:43], v[52:53], v[90:91], v[114:115] op_sel:[0,0,1] op_sel_hi:[1,1,0]
	v_pk_fma_f32 v[24:25], v[32:33], v[90:91], v[100:101] op_sel:[0,0,1] op_sel_hi:[1,1,0]
	v_pk_fma_f32 v[36:37], v[36:37], v[84:85], v[62:63] op_sel_hi:[1,0,1]
	v_pk_fma_f32 v[4:5], v[4:5], v[84:85], v[42:43] op_sel_hi:[1,0,1]
	v_pk_fma_f32 v[24:25], v[54:55], v[84:85], v[24:25] op_sel_hi:[1,0,1]
	v_pk_fma_f32 v[8:9], v[8:9], v[90:91], v[86:87] op_sel:[0,0,1] op_sel_hi:[1,1,0]
	v_pk_fma_f32 v[36:37], v[82:83], v[84:85], v[36:37] op_sel:[0,1,0]
	v_pk_fma_f32 v[4:5], v[58:59], v[84:85], v[4:5] op_sel:[0,1,0]
	v_pk_fma_f32 v[24:25], v[38:39], v[84:85], v[24:25] op_sel:[0,1,0]
	v_pk_fma_f32 v[8:9], v[34:35], v[84:85], v[8:9] op_sel_hi:[1,0,1]
	v_pk_add_f32 v[36:37], v[60:61], v[36:37]
	v_pk_add_f32 v[4:5], v[40:41], v[4:5]
	v_pk_add_f32 v[22:23], v[22:23], v[24:25]
	v_pk_fma_f32 v[6:7], v[6:7], v[84:85], v[8:9] op_sel:[0,1,0]
	v_pk_add_f32 v[10:11], v[12:13], v[10:11]
	s_waitcnt lgkmcnt(0)
	v_pk_mul_f32 v[64:65], v[98:99], v[110:111] op_sel_hi:[0,1]
	v_pk_mul_f32 v[72:73], v[72:73], v[64:65]
	v_pk_mul_f32 v[64:65], v[98:99], v[112:113] op_sel_hi:[0,1]
	v_pk_mul_f32 v[60:61], v[156:157], v[72:73] op_sel:[0,1] op_sel_hi:[1,0]
	v_pk_mul_f32 v[40:41], v[80:81], v[72:73] op_sel:[0,1] op_sel_hi:[1,0]
	v_pk_mul_f32 v[24:25], v[48:49], v[72:73] op_sel:[0,1] op_sel_hi:[1,0]
	v_pk_mul_f32 v[8:9], v[20:21], v[72:73] op_sel:[0,1] op_sel_hi:[1,0]
	v_pk_mul_f32 v[64:65], v[74:75], v[64:65]
	v_pk_fma_f32 v[60:61], v[140:141], v[72:73], v[60:61] op_sel:[0,1,1] op_sel_hi:[1,0,0]
	v_pk_fma_f32 v[40:41], v[56:57], v[72:73], v[40:41] op_sel:[0,1,1] op_sel_hi:[1,0,0]
	v_pk_fma_f32 v[24:25], v[44:45], v[72:73], v[24:25] op_sel:[0,1,1] op_sel_hi:[1,0,0]
	v_pk_fma_f32 v[8:9], v[16:17], v[72:73], v[8:9] op_sel:[0,1,1] op_sel_hi:[1,0,0]
	v_pk_fma_f32 v[60:61], v[142:143], v[64:65], v[60:61] op_sel_hi:[1,0,1]
	v_pk_fma_f32 v[40:41], v[68:69], v[64:65], v[40:41] op_sel_hi:[1,0,1]
	v_pk_fma_f32 v[24:25], v[28:29], v[64:65], v[24:25] op_sel_hi:[1,0,1]
	v_pk_fma_f32 v[0:1], v[0:1], v[64:65], v[8:9] op_sel_hi:[1,0,1]
	v_pk_fma_f32 v[60:61], v[70:71], v[64:65], v[60:61] op_sel:[0,1,0]
	v_pk_fma_f32 v[40:41], v[50:51], v[64:65], v[40:41] op_sel:[0,1,0]
	v_pk_fma_f32 v[24:25], v[30:31], v[64:65], v[24:25] op_sel:[0,1,0]
	v_pk_add_f32 v[6:7], v[10:11], v[6:7]
	v_pk_fma_f32 v[0:1], v[2:3], v[64:65], v[0:1] op_sel:[0,1,0]
	v_pk_add_f32 v[36:37], v[36:37], v[60:61]
	v_pk_add_f32 v[4:5], v[4:5], v[40:41]
	v_pk_add_f32 v[22:23], v[22:23], v[24:25]
	v_pk_add_f32 v[0:1], v[6:7], v[0:1]
	ds_bpermute_b32 v60, v240, v36
	ds_bpermute_b32 v61, v240, v37
	ds_bpermute_b32 v40, v240, v4
	ds_bpermute_b32 v41, v240, v5
	ds_bpermute_b32 v24, v240, v22
	ds_bpermute_b32 v25, v240, v23
	ds_bpermute_b32 v2, v240, v0
	ds_bpermute_b32 v3, v240, v1
	s_waitcnt lgkmcnt(6)
	v_pk_add_f32 v[36:37], v[36:37], v[60:61]
	s_waitcnt lgkmcnt(4)
	v_pk_add_f32 v[4:5], v[4:5], v[40:41]
	s_waitcnt lgkmcnt(2)
	v_pk_add_f32 v[22:23], v[22:23], v[24:25]
	ds_bpermute_b32 v60, v244, v36
	s_waitcnt lgkmcnt(1)
	v_pk_add_f32 v[0:1], v[0:1], v[2:3]
	ds_bpermute_b32 v61, v244, v37
	ds_bpermute_b32 v40, v244, v4
	ds_bpermute_b32 v41, v244, v5
	ds_bpermute_b32 v24, v244, v22
	ds_bpermute_b32 v25, v244, v23
	ds_bpermute_b32 v2, v244, v0
	ds_bpermute_b32 v3, v244, v1
	s_waitcnt lgkmcnt(6)
	v_pk_add_f32 v[36:37], v[36:37], v[60:61]
	s_waitcnt lgkmcnt(4)
	v_pk_add_f32 v[4:5], v[4:5], v[40:41]
	s_waitcnt lgkmcnt(2)
	v_pk_add_f32 v[22:23], v[22:23], v[24:25]
	ds_bpermute_b32 v60, v243, v36
	s_waitcnt lgkmcnt(1)
	v_pk_add_f32 v[0:1], v[0:1], v[2:3]
	ds_bpermute_b32 v61, v243, v37
	ds_bpermute_b32 v40, v243, v4
	ds_bpermute_b32 v41, v243, v5
	ds_bpermute_b32 v24, v243, v22
	ds_bpermute_b32 v25, v243, v23
	ds_bpermute_b32 v2, v243, v0
	ds_bpermute_b32 v3, v243, v1
	s_waitcnt lgkmcnt(6)
	v_pk_add_f32 v[36:37], v[36:37], v[60:61]
	s_waitcnt lgkmcnt(4)
	v_pk_add_f32 v[4:5], v[4:5], v[40:41]
	s_waitcnt lgkmcnt(2)
	v_pk_add_f32 v[22:23], v[22:23], v[24:25]
	ds_bpermute_b32 v60, v245, v36
	s_waitcnt lgkmcnt(1)
	v_pk_add_f32 v[0:1], v[0:1], v[2:3]
	ds_bpermute_b32 v61, v245, v37
	ds_bpermute_b32 v40, v245, v4
	ds_bpermute_b32 v41, v245, v5
	ds_bpermute_b32 v24, v245, v22
	ds_bpermute_b32 v25, v245, v23
	ds_bpermute_b32 v2, v245, v0
	ds_bpermute_b32 v3, v245, v1
	s_waitcnt lgkmcnt(6)
	v_pk_add_f32 v[36:37], v[36:37], v[60:61]
	s_waitcnt lgkmcnt(4)
	v_pk_add_f32 v[4:5], v[4:5], v[40:41]
	s_waitcnt lgkmcnt(2)
	v_pk_add_f32 v[22:23], v[22:23], v[24:25]
	ds_bpermute_b32 v60, v242, v36
	s_waitcnt lgkmcnt(1)
	v_pk_add_f32 v[0:1], v[0:1], v[2:3]
	ds_bpermute_b32 v61, v242, v37
	ds_bpermute_b32 v40, v242, v4
	ds_bpermute_b32 v41, v242, v5
	ds_bpermute_b32 v24, v242, v22
	ds_bpermute_b32 v25, v242, v23
	ds_bpermute_b32 v2, v242, v0
	ds_bpermute_b32 v3, v242, v1
	s_waitcnt lgkmcnt(6)
	v_pk_add_f32 v[36:37], v[36:37], v[60:61]
	s_waitcnt lgkmcnt(4)
	v_pk_add_f32 v[4:5], v[4:5], v[40:41]
	s_waitcnt lgkmcnt(2)
	v_pk_add_f32 v[22:23], v[22:23], v[24:25]
	ds_bpermute_b32 v60, v241, v36
	s_waitcnt lgkmcnt(1)
	v_pk_add_f32 v[0:1], v[0:1], v[2:3]
	ds_bpermute_b32 v61, v241, v37
	ds_bpermute_b32 v40, v241, v4
	ds_bpermute_b32 v41, v241, v5
	ds_bpermute_b32 v24, v241, v22
	ds_bpermute_b32 v25, v241, v23
	ds_bpermute_b32 v2, v241, v0
	ds_bpermute_b32 v3, v241, v1
	v_cvt_pk_bf16_f32 v74, v72, v73
	v_cvt_pk_bf16_f32 v75, v64, v65
	global_store_dwordx2 v[128:129], v[74:75], off offset:1536
	s_and_saveexec_b64 s[8:9], s[4:5]
	s_cbranch_execz .LBB0_41
	s_load_dwordx16 s[52:67], s[0:1], 0x140
	s_waitcnt lgkmcnt(0)
	s_load_dwordx16 s[60:75], s[0:1], 0x0
	v_lshlrev_b64 v[6:7], 5, v[166:167]
	v_pk_add_f32 v[8:9], v[4:5], v[40:41]
	v_pk_add_f32 v[4:5], v[22:23], v[24:25]
	v_lshl_add_u64 v[10:11], s[58:59], 0, v[6:7]
	v_pk_add_f32 v[6:7], v[36:37], v[60:61]
	global_store_dwordx4 v[10:11], v[6:9], off
	s_nop 1
	v_pk_add_f32 v[6:7], v[0:1], v[2:3]
	global_store_dwordx4 v[10:11], v[4:7], off offset:16
